# weight-conversion tr_tile: the 4 nontemporal row loads issued back to back with counted vmcnt instead of load-wait-write serialisation (10 instances)
# baseline (speedup 1.0000x reference)
.LBB0_173:
	s_add_i32 s0, s50, 0xf2c0
	s_and_b32 s1, s0, 0xffff
	s_mul_i32 s1, s1, 0xba2f
	s_lshr_b32 s1, s1, 21
	s_mul_i32 s26, s1, 44
	s_sub_i32 s0, s0, s26
	s_lshl_b32 s0, s0, 6
	v_mov_b32_e32 v43, v218
	s_and_b32 s0, s0, 0xffc0
	s_lshl_b32 s26, s1, 8
	v_ashrrev_i32_e32 v36, 4, v43
	s_add_u32 s26, s28, s26
	v_lshlrev_b32_e32 v48, 4, v43
	v_add_u32_e32 v46, s0, v36
	s_addc_u32 s27, s30, 0
	v_and_b32_e32 v184, 0xf0, v48
	v_ashrrev_i32_e32 v47, 31, v46
	v_lshl_add_u64 v[44:45], s[26:27], 0, v[184:185]
	v_lshlrev_b64 v[34:35], 12, v[46:47]
	v_lshl_add_u64 v[34:35], v[44:45], 0, v[34:35]
	v_mul_lo_u32 v36, v36, s90
	v_add3_u32 v47, s2, v36, v184
	global_load_dwordx4 v[60:63], v[34:35], off nt
	s_lshl_b32 s88, s0, 1
	v_add_u32_e32 v34, 16, v46
	v_ashrrev_i32_e32 v35, 31, v34
	v_lshlrev_b64 v[34:35], 12, v[34:35]
	v_lshl_add_u64 v[34:35], v[44:45], 0, v[34:35]
	global_load_dwordx4 v[64:67], v[34:35], off nt
	v_add_u32_e32 v34, 32, v46
	v_ashrrev_i32_e32 v35, 31, v34
	v_lshlrev_b64 v[34:35], 12, v[34:35]
	v_lshl_add_u64 v[34:35], v[44:45], 0, v[34:35]
	global_load_dwordx4 v[68:71], v[34:35], off nt
	v_add_u32_e32 v34, 48, v46
	v_ashrrev_i32_e32 v35, 31, v34
	v_lshlrev_b64 v[34:35], 12, v[34:35]
	v_lshl_add_u64 v[34:35], v[44:45], 0, v[34:35]
	global_load_dwordx4 v[72:75], v[34:35], off nt
	s_waitcnt vmcnt(3)
	ds_write2_b32 v47, v60, v61 offset1:1
	ds_write2_b32 v47, v62, v63 offset0:2 offset1:3
	s_waitcnt vmcnt(2)
	v_add_u32_e32 v58, 0x1040, v47
	ds_write2_b32 v58, v64, v65 offset1:1
	v_add_u32_e32 v58, 0x1048, v47
	ds_write2_b32 v58, v66, v67 offset1:1
	s_waitcnt vmcnt(1)
	v_add_u32_e32 v58, 0x2080, v47
	ds_write2_b32 v58, v68, v69 offset1:1
	v_add_u32_e32 v58, 0x2088, v47
	ds_write2_b32 v58, v70, v71 offset1:1
	s_waitcnt vmcnt(0)
	v_add_u32_e32 v58, 0x30c0, v47
	ds_write2_b32 v58, v72, v73 offset1:1
	v_add_u32_e32 v58, 0x30c8, v47
	ds_write2_b32 v58, v74, v75 offset1:1
	v_and_b32_e32 v36, 48, v48
	v_ashrrev_i32_e32 v34, 2, v43
	v_mul_u32_u24_e32 v35, 0x104, v36
	v_and_b32_e32 v37, -4, v43
	v_add3_u32 v43, s2, v35, v37
	v_lshl_add_u32 v37, s1, 6, v34
	v_mov_b64_e32 v[34:35], s[46:47]
	s_movk_i32 s1, 0x1600
	v_mad_i64_i32 v[34:35], s[26:27], v37, s1, v[34:35]
	v_lshl_add_u64 v[34:35], v[34:35], 0, s[88:89]
	v_lshlrev_b32_e32 v184, 1, v36
	s_waitcnt lgkmcnt(0)
	s_barrier
	v_lshl_add_u64 v[44:45], v[34:35], 0, v[184:185]
	ds_read2_b32 v[34:35], v43 offset1:65
	ds_read2_b32 v[36:37], v43 offset0:130 offset1:195
	v_add_u32_e32 v46, 0x400, v43
	s_waitcnt lgkmcnt(1)
	v_cvt_pk_bf16_f32 v34, v34, v35
	s_waitcnt lgkmcnt(0)
	v_cvt_pk_bf16_f32 v35, v36, v37
	ds_read2_b32 v[36:37], v46 offset0:4 offset1:69
	s_waitcnt lgkmcnt(0)
	v_cvt_pk_bf16_f32 v36, v36, v37
	ds_read2_b32 v[46:47], v46 offset0:134 offset1:199
	s_waitcnt lgkmcnt(0)
	v_cvt_pk_bf16_f32 v37, v46, v47
	global_store_dwordx4 v[44:45], v[34:37], off
	s_nop 1
	v_add_u32_e32 v36, 0x800, v43
	v_add_u32_e32 v43, 0xc00, v43
	ds_read2_b32 v[34:35], v36 offset0:8 offset1:73
	ds_read2_b32 v[36:37], v36 offset0:138 offset1:203
	ds_read2_b32 v[46:47], v43 offset0:12 offset1:77
	ds_read2_b32 v[48:49], v43 offset0:142 offset1:207
	s_waitcnt lgkmcnt(3)
	v_cvt_pk_bf16_f32 v34, v34, v35
	s_waitcnt lgkmcnt(2)
	v_cvt_pk_bf16_f32 v35, v36, v37
	s_waitcnt lgkmcnt(1)
	v_cvt_pk_bf16_f32 v36, v46, v47
	s_waitcnt lgkmcnt(0)
	v_cvt_pk_bf16_f32 v37, v48, v49
	global_store_dwordx4 v[44:45], v[34:37], off offset:16
	s_barrier

.LBB0_175:
	s_andn2_b64 vcc, exec, s[0:1]
	s_cbranch_vccnz .LBB0_177
	s_lshl_b32 s1, s50, 2
	s_and_b32 s1, s1, 0x3fc0
	s_lshl_b32 s0, s50, 6
	s_add_i32 s88, s1, 0xffffe100
	s_and_b32 s0, s0, 0x3c0
	v_mov_b32_e32 v43, v218
	s_lshl_b64 s[26:27], s[88:89], 2
	s_add_u32 s26, s31, s26
	v_lshlrev_b32_e32 v46, 4, v43
	v_ashrrev_i32_e32 v36, 4, v43
	s_addc_u32 s27, s34, s27
	v_and_b32_e32 v184, 0xf0, v46
	v_lshl_add_u64 v[44:45], s[26:27], 0, v[184:185]
	v_add_u32_e32 v47, s0, v36
	s_movk_i32 s1, 0x5800
	v_mad_i64_i32 v[34:35], s[26:27], v47, s1, v[44:45]
	v_mul_lo_u32 v36, v36, s90
	v_add3_u32 v48, s2, v36, v184
	global_load_dwordx4 v[60:63], v[34:35], off nt
	v_add_u32_e32 v34, 16, v47
	v_mad_i64_i32 v[34:35], s[26:27], v34, s1, v[44:45]
	global_load_dwordx4 v[64:67], v[34:35], off nt
	v_add_u32_e32 v34, 32, v47
	v_mad_i64_i32 v[34:35], s[26:27], v34, s1, v[44:45]
	global_load_dwordx4 v[68:71], v[34:35], off nt
	v_add_u32_e32 v34, 48, v47
	v_mad_i64_i32 v[34:35], s[26:27], v34, s1, v[44:45]
	global_load_dwordx4 v[72:75], v[34:35], off nt
	s_movk_i32 s1, 0xaff
	s_waitcnt vmcnt(3)
	ds_write2_b32 v48, v60, v61 offset1:1
	ds_write2_b32 v48, v62, v63 offset0:2 offset1:3
	s_waitcnt vmcnt(2)
	v_add_u32_e32 v58, 0x1040, v48
	ds_write2_b32 v58, v64, v65 offset1:1
	v_add_u32_e32 v58, 0x1048, v48
	ds_write2_b32 v58, v66, v67 offset1:1
	s_waitcnt vmcnt(1)
	v_add_u32_e32 v58, 0x2080, v48
	ds_write2_b32 v58, v68, v69 offset1:1
	v_add_u32_e32 v58, 0x2088, v48
	ds_write2_b32 v58, v70, v71 offset1:1
	s_waitcnt vmcnt(0)
	v_add_u32_e32 v58, 0x30c0, v48
	ds_write2_b32 v58, v72, v73 offset1:1
	v_add_u32_e32 v58, 0x30c8, v48
	ds_write2_b32 v58, v74, v75 offset1:1
	v_ashrrev_i32_e32 v34, 2, v43
	v_and_b32_e32 v36, 48, v46
	v_mul_u32_u24_e32 v35, 0x104, v36
	v_and_b32_e32 v37, -4, v43
	v_add_u32_e32 v34, s88, v34
	v_add3_u32 v43, s2, v35, v37
	v_cmp_lt_i32_e32 vcc, s1, v34
	v_add_u32_e32 v35, 0xfffff500, v34
	v_mov_b32_e32 v37, 0x80
	v_cndmask_b32_e32 v34, v34, v35, vcc
	v_lshlrev_b32_e32 v35, 1, v34
	v_and_b32_e32 v35, 0xffffff00, v35
	v_cndmask_b32_e32 v37, 0, v37, vcc
	v_and_b32_e32 v34, 0x7f, v34
	v_or3_b32 v34, v34, v37, v35
	v_ashrrev_i32_e32 v35, 31, v34
	v_lshlrev_b64 v[34:35], 11, v[34:35]
	v_lshl_add_u64 v[34:35], s[44:45], 0, v[34:35]
	s_lshl_b32 s88, s0, 1
	v_lshl_add_u64 v[34:35], v[34:35], 0, s[88:89]
	v_lshlrev_b32_e32 v184, 1, v36
	s_waitcnt lgkmcnt(0)
	s_barrier
	v_lshl_add_u64 v[44:45], v[34:35], 0, v[184:185]
	ds_read2_b32 v[34:35], v43 offset1:65
	ds_read2_b32 v[36:37], v43 offset0:130 offset1:195
	v_add_u32_e32 v46, 0x400, v43
	s_waitcnt lgkmcnt(1)
	v_cvt_pk_bf16_f32 v34, v34, v35
	s_waitcnt lgkmcnt(0)
	v_cvt_pk_bf16_f32 v35, v36, v37
	ds_read2_b32 v[36:37], v46 offset0:4 offset1:69
	s_waitcnt lgkmcnt(0)
	v_cvt_pk_bf16_f32 v36, v36, v37
	ds_read2_b32 v[46:47], v46 offset0:134 offset1:199
	s_waitcnt lgkmcnt(0)
	v_cvt_pk_bf16_f32 v37, v46, v47
	global_store_dwordx4 v[44:45], v[34:37], off
	s_nop 1
	v_add_u32_e32 v36, 0x800, v43
	v_add_u32_e32 v43, 0xc00, v43
	ds_read2_b32 v[34:35], v36 offset0:8 offset1:73
	ds_read2_b32 v[36:37], v36 offset0:138 offset1:203
	ds_read2_b32 v[46:47], v43 offset0:12 offset1:77
	ds_read2_b32 v[48:49], v43 offset0:142 offset1:207
	s_waitcnt lgkmcnt(3)
	v_cvt_pk_bf16_f32 v34, v34, v35
	s_waitcnt lgkmcnt(2)
	v_cvt_pk_bf16_f32 v35, v36, v37
	s_waitcnt lgkmcnt(1)
	v_cvt_pk_bf16_f32 v36, v46, v47
	s_waitcnt lgkmcnt(0)
	v_cvt_pk_bf16_f32 v37, v48, v49
	global_store_dwordx4 v[44:45], v[34:37], off offset:16
	s_barrier

.LBB0_178:
	s_andn2_b64 vcc, exec, s[0:1]
	s_cbranch_vccnz .LBB0_180
	s_lshl_b32 s1, s50, 2
	s_and_b32 s1, s1, 0x1fc0
	s_lshl_b32 s0, s50, 6
	s_add_i32 s88, s1, 0xffffe500
	v_mov_b32_e32 v43, v218
	s_and_b32 s0, s0, 0x3c0
	s_lshl_b64 s[26:27], s[88:89], 2
	v_ashrrev_i32_e32 v36, 4, v43
	s_add_u32 s26, s22, s26
	v_lshlrev_b32_e32 v48, 4, v43
	v_add_u32_e32 v46, s0, v36
	s_addc_u32 s27, s23, s27
	v_and_b32_e32 v184, 0xf0, v48
	v_ashrrev_i32_e32 v47, 31, v46
	v_lshl_add_u64 v[44:45], s[26:27], 0, v[184:185]
	v_lshlrev_b64 v[34:35], 12, v[46:47]
	v_lshl_add_u64 v[34:35], v[44:45], 0, v[34:35]
	v_mul_lo_u32 v36, v36, s90
	v_add3_u32 v47, s2, v36, v184
	global_load_dwordx4 v[60:63], v[34:35], off nt
	v_add_u32_e32 v34, 16, v46
	v_ashrrev_i32_e32 v35, 31, v34
	v_lshlrev_b64 v[34:35], 12, v[34:35]
	v_lshl_add_u64 v[34:35], v[44:45], 0, v[34:35]
	global_load_dwordx4 v[64:67], v[34:35], off nt
	v_add_u32_e32 v34, 32, v46
	v_ashrrev_i32_e32 v35, 31, v34
	v_lshlrev_b64 v[34:35], 12, v[34:35]
	v_lshl_add_u64 v[34:35], v[44:45], 0, v[34:35]
	global_load_dwordx4 v[68:71], v[34:35], off nt
	v_add_u32_e32 v34, 48, v46
	v_ashrrev_i32_e32 v35, 31, v34
	v_lshlrev_b64 v[34:35], 12, v[34:35]
	v_lshl_add_u64 v[34:35], v[44:45], 0, v[34:35]
	global_load_dwordx4 v[72:75], v[34:35], off nt
	s_waitcnt vmcnt(3)
	ds_write2_b32 v47, v60, v61 offset1:1
	ds_write2_b32 v47, v62, v63 offset0:2 offset1:3
	s_waitcnt vmcnt(2)
	v_add_u32_e32 v58, 0x1040, v47
	ds_write2_b32 v58, v64, v65 offset1:1
	v_add_u32_e32 v58, 0x1048, v47
	ds_write2_b32 v58, v66, v67 offset1:1
	s_waitcnt vmcnt(1)
	v_add_u32_e32 v58, 0x2080, v47
	ds_write2_b32 v58, v68, v69 offset1:1
	v_add_u32_e32 v58, 0x2088, v47
	ds_write2_b32 v58, v70, v71 offset1:1
	s_waitcnt vmcnt(0)
	v_add_u32_e32 v58, 0x30c0, v47
	ds_write2_b32 v58, v72, v73 offset1:1
	v_add_u32_e32 v58, 0x30c8, v47
	ds_write2_b32 v58, v74, v75 offset1:1
	v_ashrrev_i32_e32 v34, 2, v43
	v_and_b32_e32 v36, 48, v48
	v_mul_u32_u24_e32 v35, 0x104, v36
	v_and_b32_e32 v37, -4, v43
	v_add_u32_e32 v34, s88, v34
	v_add3_u32 v43, s2, v35, v37
	v_ashrrev_i32_e32 v35, 31, v34
	v_lshlrev_b64 v[34:35], 11, v[34:35]
	v_lshl_add_u64 v[34:35], s[42:43], 0, v[34:35]
	s_lshl_b32 s88, s0, 1
	v_lshl_add_u64 v[34:35], v[34:35], 0, s[88:89]
	v_lshlrev_b32_e32 v184, 1, v36
	s_waitcnt lgkmcnt(0)
	s_barrier
	v_lshl_add_u64 v[44:45], v[34:35], 0, v[184:185]
	ds_read2_b32 v[34:35], v43 offset1:65
	ds_read2_b32 v[36:37], v43 offset0:130 offset1:195
	v_add_u32_e32 v46, 0x400, v43
	s_waitcnt lgkmcnt(1)
	v_cvt_pk_bf16_f32 v34, v34, v35
	s_waitcnt lgkmcnt(0)
	v_cvt_pk_bf16_f32 v35, v36, v37
	ds_read2_b32 v[36:37], v46 offset0:4 offset1:69
	s_waitcnt lgkmcnt(0)
	v_cvt_pk_bf16_f32 v36, v36, v37
	ds_read2_b32 v[46:47], v46 offset0:134 offset1:199
	s_waitcnt lgkmcnt(0)
	v_cvt_pk_bf16_f32 v37, v46, v47
	global_store_dwordx4 v[44:45], v[34:37], off
	s_nop 1
	v_add_u32_e32 v36, 0x800, v43
	v_add_u32_e32 v43, 0xc00, v43
	ds_read2_b32 v[34:35], v36 offset0:8 offset1:73
	ds_read2_b32 v[36:37], v36 offset0:138 offset1:203
	ds_read2_b32 v[46:47], v43 offset0:12 offset1:77
	ds_read2_b32 v[48:49], v43 offset0:142 offset1:207
	s_waitcnt lgkmcnt(3)
	v_cvt_pk_bf16_f32 v34, v34, v35
	s_waitcnt lgkmcnt(2)
	v_cvt_pk_bf16_f32 v35, v36, v37
	s_waitcnt lgkmcnt(1)
	v_cvt_pk_bf16_f32 v36, v46, v47
	s_waitcnt lgkmcnt(0)
	v_cvt_pk_bf16_f32 v37, v48, v49
	global_store_dwordx4 v[44:45], v[34:37], off offset:16
	s_barrier

.LBB0_181:
	s_andn2_b64 vcc, exec, s[0:1]
	s_cbranch_vccnz .LBB0_183
	s_add_i32 s0, s50, 0xfffffa00
	s_lshr_b32 s88, s0, 6
	s_lshl_b64 s[0:1], s[88:89], 20
	s_add_u32 s33, s52, s0
	s_addc_u32 s35, s53, s1
	s_lshl_b32 s0, s50, 6
	s_and_b32 s26, s0, 0xc0
	s_lshl_b32 s0, s50, 4
	s_and_b32 s27, s0, 0x3c0
	s_lshl_b64 s[0:1], s[88:89], 19
	s_add_u32 s0, s40, s0
	v_mov_b32_e32 v43, v218
	s_addc_u32 s1, s41, s1
	s_lshl_b32 s55, s27, 2
	v_ashrrev_i32_e32 v36, 4, v43
	s_add_u32 s58, s33, s55
	v_lshlrev_b32_e32 v48, 4, v43
	v_add_u32_e32 v46, s26, v36
	s_addc_u32 s59, s35, 0
	v_and_b32_e32 v184, 0xf0, v48
	v_ashrrev_i32_e32 v47, 31, v46
	v_lshl_add_u64 v[44:45], s[58:59], 0, v[184:185]
	v_lshlrev_b64 v[34:35], 12, v[46:47]
	v_lshl_add_u64 v[34:35], v[44:45], 0, v[34:35]
	v_mul_lo_u32 v36, v36, s90
	v_add3_u32 v47, s2, v36, v184
	global_load_dwordx4 v[60:63], v[34:35], off nt
	s_lshl_b32 s88, s26, 1
	s_movk_i32 s33, 0x3fff
	v_add_u32_e32 v34, 16, v46
	v_ashrrev_i32_e32 v35, 31, v34
	v_lshlrev_b64 v[34:35], 12, v[34:35]
	v_lshl_add_u64 v[34:35], v[44:45], 0, v[34:35]
	global_load_dwordx4 v[64:67], v[34:35], off nt
	v_add_u32_e32 v34, 32, v46
	v_ashrrev_i32_e32 v35, 31, v34
	v_lshlrev_b64 v[34:35], 12, v[34:35]
	v_lshl_add_u64 v[34:35], v[44:45], 0, v[34:35]
	global_load_dwordx4 v[68:71], v[34:35], off nt
	v_add_u32_e32 v34, 48, v46
	v_ashrrev_i32_e32 v35, 31, v34
	v_lshlrev_b64 v[34:35], 12, v[34:35]
	v_lshl_add_u64 v[34:35], v[44:45], 0, v[34:35]
	global_load_dwordx4 v[72:75], v[34:35], off nt
	s_waitcnt vmcnt(3)
	ds_write2_b32 v47, v60, v61 offset1:1
	ds_write2_b32 v47, v62, v63 offset0:2 offset1:3
	s_waitcnt vmcnt(2)
	v_add_u32_e32 v58, 0x1040, v47
	ds_write2_b32 v58, v64, v65 offset1:1
	v_add_u32_e32 v58, 0x1048, v47
	ds_write2_b32 v58, v66, v67 offset1:1
	s_waitcnt vmcnt(1)
	v_add_u32_e32 v58, 0x2080, v47
	ds_write2_b32 v58, v68, v69 offset1:1
	v_add_u32_e32 v58, 0x2088, v47
	ds_write2_b32 v58, v70, v71 offset1:1
	s_waitcnt vmcnt(0)
	v_add_u32_e32 v58, 0x30c0, v47
	ds_write2_b32 v58, v72, v73 offset1:1
	v_add_u32_e32 v58, 0x30c8, v47
	ds_write2_b32 v58, v74, v75 offset1:1
	v_ashrrev_i32_e32 v34, 2, v43
	v_and_b32_e32 v36, 48, v48
	v_mul_u32_u24_e32 v35, 0x104, v36
	v_and_b32_e32 v37, -4, v43
	v_add_u32_e32 v34, s27, v34
	v_add3_u32 v43, s2, v35, v37
	v_ashrrev_i32_e32 v35, 31, v34
	v_lshlrev_b64 v[34:35], 9, v[34:35]
	v_lshl_add_u64 v[34:35], s[0:1], 0, v[34:35]
	v_lshl_add_u64 v[34:35], v[34:35], 0, s[88:89]
	v_lshlrev_b32_e32 v184, 1, v36
	s_waitcnt lgkmcnt(0)
	s_barrier
	v_lshl_add_u64 v[44:45], v[34:35], 0, v[184:185]
	ds_read2_b32 v[34:35], v43 offset1:65
	ds_read2_b32 v[36:37], v43 offset0:130 offset1:195
	v_add_u32_e32 v46, 0x400, v43
	s_waitcnt lgkmcnt(1)
	v_cvt_pk_bf16_f32 v34, v34, v35
	s_waitcnt lgkmcnt(0)
	v_cvt_pk_bf16_f32 v35, v36, v37
	ds_read2_b32 v[36:37], v46 offset0:4 offset1:69
	s_waitcnt lgkmcnt(0)
	v_cvt_pk_bf16_f32 v36, v36, v37
	ds_read2_b32 v[46:47], v46 offset0:134 offset1:199
	s_waitcnt lgkmcnt(0)
	v_cvt_pk_bf16_f32 v37, v46, v47
	global_store_dwordx4 v[44:45], v[34:37], off
	s_nop 1
	v_add_u32_e32 v36, 0x800, v43
	v_add_u32_e32 v43, 0xc00, v43
	ds_read2_b32 v[34:35], v36 offset0:8 offset1:73
	ds_read2_b32 v[36:37], v36 offset0:138 offset1:203
	ds_read2_b32 v[46:47], v43 offset0:12 offset1:77
	ds_read2_b32 v[48:49], v43 offset0:142 offset1:207
	s_waitcnt lgkmcnt(3)
	v_cvt_pk_bf16_f32 v34, v34, v35
	s_waitcnt lgkmcnt(2)
	v_cvt_pk_bf16_f32 v35, v36, v37
	s_waitcnt lgkmcnt(1)
	v_cvt_pk_bf16_f32 v36, v46, v47
	s_waitcnt lgkmcnt(0)
	v_cvt_pk_bf16_f32 v37, v48, v49
	global_store_dwordx4 v[44:45], v[34:37], off offset:16
	s_barrier

.LBB0_184:
	s_andn2_b64 vcc, exec, s[0:1]
	s_cbranch_vccnz .LBB0_152
	s_lshl_b32 s0, s50, 2
	s_and_b32 s26, s0, 0xffffffc0
	s_add_i32 s0, s26, 0x100
	s_cmpk_lt_i32 s26, 0x700
	s_cselect_b32 s0, s26, s0
	s_lshl_b32 s1, s50, 6
	s_and_b32 s27, s1, 0x3c0
	s_ashr_i32 s1, s0, 31
	v_mov_b32_e32 v43, v218
	s_lshl_b64 s[0:1], s[0:1], 2
	s_add_u32 s0, s48, s0
	v_lshlrev_b32_e32 v46, 4, v43
	v_ashrrev_i32_e32 v36, 4, v43
	s_addc_u32 s1, s49, s1
	v_and_b32_e32 v184, 0xf0, v46
	v_lshl_add_u64 v[44:45], s[0:1], 0, v[184:185]
	v_add_u32_e32 v47, s27, v36
	s_movk_i32 s4, 0x6400
	v_mad_i64_i32 v[34:35], s[0:1], v47, s4, v[44:45]
	v_mul_lo_u32 v36, v36, s90
	v_add3_u32 v48, s2, v36, v184
	global_load_dwordx4 v[60:63], v[34:35], off nt
	s_lshl_b32 s88, s27, 1
	v_add_u32_e32 v34, 16, v47
	v_mad_i64_i32 v[34:35], s[0:1], v34, s4, v[44:45]
	global_load_dwordx4 v[64:67], v[34:35], off nt
	v_add_u32_e32 v34, 32, v47
	v_mad_i64_i32 v[34:35], s[0:1], v34, s4, v[44:45]
	global_load_dwordx4 v[68:71], v[34:35], off nt
	v_add_u32_e32 v34, 48, v47
	v_mad_i64_i32 v[34:35], s[0:1], v34, s4, v[44:45]
	global_load_dwordx4 v[72:75], v[34:35], off nt
	s_waitcnt vmcnt(3)
	ds_write2_b32 v48, v60, v61 offset1:1
	ds_write2_b32 v48, v62, v63 offset0:2 offset1:3
	s_waitcnt vmcnt(2)
	v_add_u32_e32 v58, 0x1040, v48
	ds_write2_b32 v58, v64, v65 offset1:1
	v_add_u32_e32 v58, 0x1048, v48
	ds_write2_b32 v58, v66, v67 offset1:1
	s_waitcnt vmcnt(1)
	v_add_u32_e32 v58, 0x2080, v48
	ds_write2_b32 v58, v68, v69 offset1:1
	v_add_u32_e32 v58, 0x2088, v48
	ds_write2_b32 v58, v70, v71 offset1:1
	s_waitcnt vmcnt(0)
	v_add_u32_e32 v58, 0x30c0, v48
	ds_write2_b32 v58, v72, v73 offset1:1
	v_add_u32_e32 v58, 0x30c8, v48
	ds_write2_b32 v58, v74, v75 offset1:1
	v_ashrrev_i32_e32 v34, 2, v43
	v_and_b32_e32 v36, 48, v46
	v_mul_u32_u24_e32 v35, 0x104, v36
	v_and_b32_e32 v37, -4, v43
	v_add_u32_e32 v34, s26, v34
	v_add3_u32 v43, s2, v35, v37
	v_ashrrev_i32_e32 v35, 31, v34
	v_lshlrev_b64 v[34:35], 11, v[34:35]
	v_lshl_add_u64 v[34:35], s[38:39], 0, v[34:35]
	v_lshl_add_u64 v[34:35], v[34:35], 0, s[88:89]
	v_lshlrev_b32_e32 v184, 1, v36
	s_waitcnt lgkmcnt(0)
	s_barrier
	v_lshl_add_u64 v[44:45], v[34:35], 0, v[184:185]
	ds_read2_b32 v[34:35], v43 offset1:65
	ds_read2_b32 v[36:37], v43 offset0:130 offset1:195
	v_add_u32_e32 v46, 0x400, v43
	s_waitcnt lgkmcnt(1)
	v_cvt_pk_bf16_f32 v34, v34, v35
	s_waitcnt lgkmcnt(0)
	v_cvt_pk_bf16_f32 v35, v36, v37
	ds_read2_b32 v[36:37], v46 offset0:4 offset1:69
	s_waitcnt lgkmcnt(0)
	v_cvt_pk_bf16_f32 v36, v36, v37
	ds_read2_b32 v[46:47], v46 offset0:134 offset1:199
	s_waitcnt lgkmcnt(0)
	v_cvt_pk_bf16_f32 v37, v46, v47
	global_store_dwordx4 v[44:45], v[34:37], off
	s_nop 1
	v_add_u32_e32 v36, 0x800, v43
	v_add_u32_e32 v43, 0xc00, v43
	ds_read2_b32 v[34:35], v36 offset0:8 offset1:73
	ds_read2_b32 v[36:37], v36 offset0:138 offset1:203
	ds_read2_b32 v[46:47], v43 offset0:12 offset1:77
	ds_read2_b32 v[48:49], v43 offset0:142 offset1:207
	s_waitcnt lgkmcnt(3)
	v_cvt_pk_bf16_f32 v34, v34, v35
	s_waitcnt lgkmcnt(2)
	v_cvt_pk_bf16_f32 v35, v36, v37
	s_waitcnt lgkmcnt(1)
	v_cvt_pk_bf16_f32 v36, v46, v47
	s_waitcnt lgkmcnt(0)
	v_cvt_pk_bf16_f32 v37, v48, v49
	global_store_dwordx4 v[44:45], v[34:37], off offset:16
	s_barrier
	s_branch .LBB0_152

.LBB0_506:
	s_add_i32 s0, s20, 0xf2c0
	s_and_b32 s1, s0, 0xffff
	s_mul_i32 s1, s1, 0xba2f
	s_lshr_b32 s1, s1, 21
	s_mul_i32 s23, s1, 44
	s_sub_i32 s0, s0, s23
	s_lshl_b32 s0, s0, 6
	v_mov_b32_e32 v43, v218
	v_readlane_b32 s56, v253, 48
	s_and_b32 s0, s0, 0xffc0
	s_lshl_b32 s23, s1, 8
	v_ashrrev_i32_e32 v36, 4, v43
	v_readlane_b32 s70, v253, 62
	v_readlane_b32 s71, v253, 63
	s_add_u32 s26, s70, s23
	v_lshlrev_b32_e32 v48, 4, v43
	v_add_u32_e32 v46, s0, v36
	s_addc_u32 s27, s71, 0
	v_and_b32_e32 v184, 0xf0, v48
	v_ashrrev_i32_e32 v47, 31, v46
	v_lshl_add_u64 v[44:45], s[26:27], 0, v[184:185]
	v_lshlrev_b64 v[34:35], 12, v[46:47]
	v_lshl_add_u64 v[34:35], v[44:45], 0, v[34:35]
	v_mul_lo_u32 v36, v36, s34
	v_add3_u32 v47, s2, v36, v184
	global_load_dwordx4 v[60:63], v[34:35], off nt
	v_readlane_b32 s57, v253, 49
	v_readlane_b32 s58, v253, 50
	v_readlane_b32 s59, v253, 51
	v_readlane_b32 s60, v253, 52
	v_readlane_b32 s61, v253, 53
	v_readlane_b32 s62, v253, 54
	v_readlane_b32 s63, v253, 55
	v_readlane_b32 s64, v253, 56
	v_readlane_b32 s65, v253, 57
	v_readlane_b32 s66, v253, 58
	v_readlane_b32 s67, v253, 59
	v_readlane_b32 s68, v253, 60
	v_readlane_b32 s69, v253, 61
	v_readlane_b32 s56, v253, 0
	v_readlane_b32 s66, v253, 10
	v_readlane_b32 s67, v253, 11
	s_lshl_b32 s88, s0, 1
	v_readlane_b32 s70, v253, 14
	v_readlane_b32 s71, v253, 15
	s_mov_b32 s71, 0x42ce8ed0
	s_mov_b32 s70, 0xbfb8aa3b
	v_readlane_b32 s57, v253, 1
	v_readlane_b32 s58, v253, 2
	v_readlane_b32 s59, v253, 3
	v_readlane_b32 s60, v253, 4
	v_readlane_b32 s61, v253, 5
	v_readlane_b32 s62, v253, 6
	v_readlane_b32 s63, v253, 7
	v_readlane_b32 s64, v253, 8
	v_readlane_b32 s65, v253, 9
	v_readlane_b32 s68, v253, 12
	v_readlane_b32 s69, v253, 13
	v_add_u32_e32 v34, 16, v46
	v_ashrrev_i32_e32 v35, 31, v34
	v_lshlrev_b64 v[34:35], 12, v[34:35]
	v_lshl_add_u64 v[34:35], v[44:45], 0, v[34:35]
	global_load_dwordx4 v[64:67], v[34:35], off nt
	v_add_u32_e32 v34, 32, v46
	v_ashrrev_i32_e32 v35, 31, v34
	v_lshlrev_b64 v[34:35], 12, v[34:35]
	v_lshl_add_u64 v[34:35], v[44:45], 0, v[34:35]
	global_load_dwordx4 v[68:71], v[34:35], off nt
	v_add_u32_e32 v34, 48, v46
	v_ashrrev_i32_e32 v35, 31, v34
	v_lshlrev_b64 v[34:35], 12, v[34:35]
	v_lshl_add_u64 v[34:35], v[44:45], 0, v[34:35]
	global_load_dwordx4 v[72:75], v[34:35], off nt
	s_waitcnt vmcnt(3)
	ds_write2_b32 v47, v60, v61 offset1:1
	ds_write2_b32 v47, v62, v63 offset0:2 offset1:3
	s_waitcnt vmcnt(2)
	v_add_u32_e32 v58, 0x1040, v47
	ds_write2_b32 v58, v64, v65 offset1:1
	v_add_u32_e32 v58, 0x1048, v47
	ds_write2_b32 v58, v66, v67 offset1:1
	s_waitcnt vmcnt(1)
	v_add_u32_e32 v58, 0x2080, v47
	ds_write2_b32 v58, v68, v69 offset1:1
	v_add_u32_e32 v58, 0x2088, v47
	ds_write2_b32 v58, v70, v71 offset1:1
	s_waitcnt vmcnt(0)
	v_add_u32_e32 v58, 0x30c0, v47
	ds_write2_b32 v58, v72, v73 offset1:1
	v_add_u32_e32 v58, 0x30c8, v47
	ds_write2_b32 v58, v74, v75 offset1:1
	v_and_b32_e32 v36, 48, v48
	v_ashrrev_i32_e32 v34, 2, v43
	v_mul_u32_u24_e32 v35, 0x104, v36
	v_and_b32_e32 v37, -4, v43
	v_add3_u32 v43, s2, v35, v37
	v_lshl_add_u32 v37, s1, 6, v34
	v_mov_b64_e32 v[34:35], s[66:67]
	s_movk_i32 s1, 0x1600
	v_mad_i64_i32 v[34:35], s[26:27], v37, s1, v[34:35]
	v_lshl_add_u64 v[34:35], v[34:35], 0, s[88:89]
	v_lshlrev_b32_e32 v184, 1, v36
	s_waitcnt lgkmcnt(0)
	s_barrier
	v_lshl_add_u64 v[44:45], v[34:35], 0, v[184:185]
	ds_read2_b32 v[34:35], v43 offset1:65
	ds_read2_b32 v[36:37], v43 offset0:130 offset1:195
	v_add_u32_e32 v46, 0x400, v43
	s_waitcnt lgkmcnt(1)
	v_cvt_pk_bf16_f32 v34, v34, v35
	s_waitcnt lgkmcnt(0)
	v_cvt_pk_bf16_f32 v35, v36, v37
	ds_read2_b32 v[36:37], v46 offset0:4 offset1:69
	s_waitcnt lgkmcnt(0)
	v_cvt_pk_bf16_f32 v36, v36, v37
	ds_read2_b32 v[46:47], v46 offset0:134 offset1:199
	s_waitcnt lgkmcnt(0)
	v_cvt_pk_bf16_f32 v37, v46, v47
	global_store_dwordx4 v[44:45], v[34:37], off
	s_nop 1
	v_add_u32_e32 v36, 0x800, v43
	v_add_u32_e32 v43, 0xc00, v43
	ds_read2_b32 v[34:35], v36 offset0:8 offset1:73
	ds_read2_b32 v[36:37], v36 offset0:138 offset1:203
	ds_read2_b32 v[46:47], v43 offset0:12 offset1:77
	ds_read2_b32 v[48:49], v43 offset0:142 offset1:207
	s_waitcnt lgkmcnt(3)
	v_cvt_pk_bf16_f32 v34, v34, v35
	s_waitcnt lgkmcnt(2)
	v_cvt_pk_bf16_f32 v35, v36, v37
	s_waitcnt lgkmcnt(1)
	v_cvt_pk_bf16_f32 v36, v46, v47
	s_waitcnt lgkmcnt(0)
	v_cvt_pk_bf16_f32 v37, v48, v49
	global_store_dwordx4 v[44:45], v[34:37], off offset:16
	s_barrier

.LBB0_508:
	s_andn2_b64 vcc, exec, s[0:1]
	s_cbranch_vccnz .LBB0_510
	s_lshl_b32 s1, s20, 2
	s_and_b32 s1, s1, 0x3fc0
	s_lshl_b32 s0, s20, 6
	s_add_i32 s88, s1, 0xffffe100
	v_readlane_b32 s56, v253, 48
	s_and_b32 s0, s0, 0x3c0
	v_mov_b32_e32 v43, v218
	s_lshl_b64 s[26:27], s[88:89], 2
	v_readlane_b32 s68, v253, 60
	v_readlane_b32 s69, v253, 61
	s_add_u32 s26, s68, s26
	v_lshlrev_b32_e32 v46, 4, v43
	v_ashrrev_i32_e32 v36, 4, v43
	s_addc_u32 s27, s69, s27
	v_and_b32_e32 v184, 0xf0, v46
	v_lshl_add_u64 v[44:45], s[26:27], 0, v[184:185]
	v_add_u32_e32 v47, s0, v36
	s_movk_i32 s1, 0x5800
	v_mad_i64_i32 v[34:35], s[26:27], v47, s1, v[44:45]
	v_mul_lo_u32 v36, v36, s34
	v_add3_u32 v48, s2, v36, v184
	global_load_dwordx4 v[60:63], v[34:35], off nt
	v_readlane_b32 s4, v253, 0
	v_readlane_b32 s12, v253, 8
	v_readlane_b32 s13, v253, 9
	v_readlane_b32 s70, v253, 62
	v_readlane_b32 s71, v253, 63
	s_mov_b32 s71, 0x42ce8ed0
	s_mov_b32 s70, 0xbfb8aa3b
	v_readlane_b32 s57, v253, 49
	v_readlane_b32 s58, v253, 50
	v_readlane_b32 s59, v253, 51
	v_readlane_b32 s60, v253, 52
	v_readlane_b32 s61, v253, 53
	v_readlane_b32 s62, v253, 54
	v_readlane_b32 s63, v253, 55
	v_readlane_b32 s64, v253, 56
	v_readlane_b32 s65, v253, 57
	v_readlane_b32 s66, v253, 58
	v_readlane_b32 s67, v253, 59
	v_readlane_b32 s5, v253, 1
	v_readlane_b32 s6, v253, 2
	v_readlane_b32 s7, v253, 3
	v_readlane_b32 s8, v253, 4
	v_readlane_b32 s9, v253, 5
	v_readlane_b32 s10, v253, 6
	v_readlane_b32 s11, v253, 7
	v_readlane_b32 s14, v253, 10
	v_readlane_b32 s15, v253, 11
	v_readlane_b32 s16, v253, 12
	v_readlane_b32 s17, v253, 13
	v_readlane_b32 s18, v253, 14
	v_readlane_b32 s19, v253, 15
	v_add_u32_e32 v34, 16, v47
	v_mad_i64_i32 v[34:35], s[26:27], v34, s1, v[44:45]
	global_load_dwordx4 v[64:67], v[34:35], off nt
	v_add_u32_e32 v34, 32, v47
	v_mad_i64_i32 v[34:35], s[26:27], v34, s1, v[44:45]
	global_load_dwordx4 v[68:71], v[34:35], off nt
	v_add_u32_e32 v34, 48, v47
	v_mad_i64_i32 v[34:35], s[26:27], v34, s1, v[44:45]
	global_load_dwordx4 v[72:75], v[34:35], off nt
	s_movk_i32 s1, 0xaff
	s_waitcnt vmcnt(3)
	ds_write2_b32 v48, v60, v61 offset1:1
	ds_write2_b32 v48, v62, v63 offset0:2 offset1:3
	s_waitcnt vmcnt(2)
	v_add_u32_e32 v58, 0x1040, v48
	ds_write2_b32 v58, v64, v65 offset1:1
	v_add_u32_e32 v58, 0x1048, v48
	ds_write2_b32 v58, v66, v67 offset1:1
	s_waitcnt vmcnt(1)
	v_add_u32_e32 v58, 0x2080, v48
	ds_write2_b32 v58, v68, v69 offset1:1
	v_add_u32_e32 v58, 0x2088, v48
	ds_write2_b32 v58, v70, v71 offset1:1
	s_waitcnt vmcnt(0)
	v_add_u32_e32 v58, 0x30c0, v48
	ds_write2_b32 v58, v72, v73 offset1:1
	v_add_u32_e32 v58, 0x30c8, v48
	ds_write2_b32 v58, v74, v75 offset1:1
	v_ashrrev_i32_e32 v34, 2, v43
	v_and_b32_e32 v36, 48, v46
	v_mul_u32_u24_e32 v35, 0x104, v36
	v_and_b32_e32 v37, -4, v43
	v_add_u32_e32 v34, s88, v34
	v_add3_u32 v43, s2, v35, v37
	v_cmp_lt_i32_e32 vcc, s1, v34
	v_add_u32_e32 v35, 0xfffff500, v34
	v_mov_b32_e32 v37, 0x80
	v_cndmask_b32_e32 v34, v34, v35, vcc
	v_lshlrev_b32_e32 v35, 1, v34
	v_and_b32_e32 v35, 0xffffff00, v35
	v_cndmask_b32_e32 v37, 0, v37, vcc
	v_and_b32_e32 v34, 0x7f, v34
	v_or3_b32 v34, v34, v37, v35
	v_ashrrev_i32_e32 v35, 31, v34
	v_lshlrev_b64 v[34:35], 11, v[34:35]
	v_lshl_add_u64 v[34:35], s[12:13], 0, v[34:35]
	s_lshl_b32 s88, s0, 1
	v_lshl_add_u64 v[34:35], v[34:35], 0, s[88:89]
	v_lshlrev_b32_e32 v184, 1, v36
	s_waitcnt lgkmcnt(0)
	s_barrier
	v_lshl_add_u64 v[44:45], v[34:35], 0, v[184:185]
	ds_read2_b32 v[34:35], v43 offset1:65
	ds_read2_b32 v[36:37], v43 offset0:130 offset1:195
	v_add_u32_e32 v46, 0x400, v43
	s_waitcnt lgkmcnt(1)
	v_cvt_pk_bf16_f32 v34, v34, v35
	s_waitcnt lgkmcnt(0)
	v_cvt_pk_bf16_f32 v35, v36, v37
	ds_read2_b32 v[36:37], v46 offset0:4 offset1:69
	s_waitcnt lgkmcnt(0)
	v_cvt_pk_bf16_f32 v36, v36, v37
	ds_read2_b32 v[46:47], v46 offset0:134 offset1:199
	s_waitcnt lgkmcnt(0)
	v_cvt_pk_bf16_f32 v37, v46, v47
	global_store_dwordx4 v[44:45], v[34:37], off
	s_nop 1
	v_add_u32_e32 v36, 0x800, v43
	v_add_u32_e32 v43, 0xc00, v43
	ds_read2_b32 v[34:35], v36 offset0:8 offset1:73
	ds_read2_b32 v[36:37], v36 offset0:138 offset1:203
	ds_read2_b32 v[46:47], v43 offset0:12 offset1:77
	ds_read2_b32 v[48:49], v43 offset0:142 offset1:207
	s_waitcnt lgkmcnt(3)
	v_cvt_pk_bf16_f32 v34, v34, v35
	s_waitcnt lgkmcnt(2)
	v_cvt_pk_bf16_f32 v35, v36, v37
	s_waitcnt lgkmcnt(1)
	v_cvt_pk_bf16_f32 v36, v46, v47
	s_waitcnt lgkmcnt(0)
	v_cvt_pk_bf16_f32 v37, v48, v49
	global_store_dwordx4 v[44:45], v[34:37], off offset:16
	s_barrier

.LBB0_511:
	s_andn2_b64 vcc, exec, s[0:1]
	s_cbranch_vccnz .LBB0_513
	s_lshl_b32 s1, s20, 2
	s_and_b32 s1, s1, 0x1fc0
	s_lshl_b32 s0, s20, 6
	s_add_i32 s88, s1, 0xffffe500
	v_mov_b32_e32 v43, v218
	v_readlane_b32 s56, v253, 48
	s_and_b32 s0, s0, 0x3c0
	s_lshl_b64 s[26:27], s[88:89], 2
	v_ashrrev_i32_e32 v36, 4, v43
	v_readlane_b32 s66, v253, 58
	v_readlane_b32 s67, v253, 59
	s_add_u32 s26, s66, s26
	v_lshlrev_b32_e32 v48, 4, v43
	v_add_u32_e32 v46, s0, v36
	s_addc_u32 s27, s67, s27
	v_and_b32_e32 v184, 0xf0, v48
	v_ashrrev_i32_e32 v47, 31, v46
	v_lshl_add_u64 v[44:45], s[26:27], 0, v[184:185]
	v_lshlrev_b64 v[34:35], 12, v[46:47]
	v_lshl_add_u64 v[34:35], v[44:45], 0, v[34:35]
	v_mul_lo_u32 v36, v36, s34
	v_add3_u32 v47, s2, v36, v184
	global_load_dwordx4 v[60:63], v[34:35], off nt
	v_readlane_b32 s4, v253, 0
	v_readlane_b32 s10, v253, 6
	v_readlane_b32 s11, v253, 7
	v_readlane_b32 s70, v253, 62
	v_readlane_b32 s71, v253, 63
	s_mov_b32 s71, 0x42ce8ed0
	s_mov_b32 s70, 0xbfb8aa3b
	v_readlane_b32 s57, v253, 49
	v_readlane_b32 s58, v253, 50
	v_readlane_b32 s59, v253, 51
	v_readlane_b32 s60, v253, 52
	v_readlane_b32 s61, v253, 53
	v_readlane_b32 s62, v253, 54
	v_readlane_b32 s63, v253, 55
	v_readlane_b32 s64, v253, 56
	v_readlane_b32 s65, v253, 57
	v_readlane_b32 s68, v253, 60
	v_readlane_b32 s69, v253, 61
	v_readlane_b32 s5, v253, 1
	v_readlane_b32 s6, v253, 2
	v_readlane_b32 s7, v253, 3
	v_readlane_b32 s8, v253, 4
	v_readlane_b32 s9, v253, 5
	v_readlane_b32 s12, v253, 8
	v_readlane_b32 s13, v253, 9
	v_readlane_b32 s14, v253, 10
	v_readlane_b32 s15, v253, 11
	v_readlane_b32 s16, v253, 12
	v_readlane_b32 s17, v253, 13
	v_readlane_b32 s18, v253, 14
	v_readlane_b32 s19, v253, 15
	v_add_u32_e32 v34, 16, v46
	v_ashrrev_i32_e32 v35, 31, v34
	v_lshlrev_b64 v[34:35], 12, v[34:35]
	v_lshl_add_u64 v[34:35], v[44:45], 0, v[34:35]
	global_load_dwordx4 v[64:67], v[34:35], off nt
	v_add_u32_e32 v34, 32, v46
	v_ashrrev_i32_e32 v35, 31, v34
	v_lshlrev_b64 v[34:35], 12, v[34:35]
	v_lshl_add_u64 v[34:35], v[44:45], 0, v[34:35]
	global_load_dwordx4 v[68:71], v[34:35], off nt
	v_add_u32_e32 v34, 48, v46
	v_ashrrev_i32_e32 v35, 31, v34
	v_lshlrev_b64 v[34:35], 12, v[34:35]
	v_lshl_add_u64 v[34:35], v[44:45], 0, v[34:35]
	global_load_dwordx4 v[72:75], v[34:35], off nt
	s_waitcnt vmcnt(3)
	ds_write2_b32 v47, v60, v61 offset1:1
	ds_write2_b32 v47, v62, v63 offset0:2 offset1:3
	s_waitcnt vmcnt(2)
	v_add_u32_e32 v58, 0x1040, v47
	ds_write2_b32 v58, v64, v65 offset1:1
	v_add_u32_e32 v58, 0x1048, v47
	ds_write2_b32 v58, v66, v67 offset1:1
	s_waitcnt vmcnt(1)
	v_add_u32_e32 v58, 0x2080, v47
	ds_write2_b32 v58, v68, v69 offset1:1
	v_add_u32_e32 v58, 0x2088, v47
	ds_write2_b32 v58, v70, v71 offset1:1
	s_waitcnt vmcnt(0)
	v_add_u32_e32 v58, 0x30c0, v47
	ds_write2_b32 v58, v72, v73 offset1:1
	v_add_u32_e32 v58, 0x30c8, v47
	ds_write2_b32 v58, v74, v75 offset1:1
	v_ashrrev_i32_e32 v34, 2, v43
	v_and_b32_e32 v36, 48, v48
	v_mul_u32_u24_e32 v35, 0x104, v36
	v_and_b32_e32 v37, -4, v43
	v_add_u32_e32 v34, s88, v34
	v_add3_u32 v43, s2, v35, v37
	v_ashrrev_i32_e32 v35, 31, v34
	v_lshlrev_b64 v[34:35], 11, v[34:35]
	v_lshl_add_u64 v[34:35], s[10:11], 0, v[34:35]
	s_lshl_b32 s88, s0, 1
	v_lshl_add_u64 v[34:35], v[34:35], 0, s[88:89]
	v_lshlrev_b32_e32 v184, 1, v36
	s_waitcnt lgkmcnt(0)
	s_barrier
	v_lshl_add_u64 v[44:45], v[34:35], 0, v[184:185]
	ds_read2_b32 v[34:35], v43 offset1:65
	ds_read2_b32 v[36:37], v43 offset0:130 offset1:195
	v_add_u32_e32 v46, 0x400, v43
	s_waitcnt lgkmcnt(1)
	v_cvt_pk_bf16_f32 v34, v34, v35
	s_waitcnt lgkmcnt(0)
	v_cvt_pk_bf16_f32 v35, v36, v37
	ds_read2_b32 v[36:37], v46 offset0:4 offset1:69
	s_waitcnt lgkmcnt(0)
	v_cvt_pk_bf16_f32 v36, v36, v37
	ds_read2_b32 v[46:47], v46 offset0:134 offset1:199
	s_waitcnt lgkmcnt(0)
	v_cvt_pk_bf16_f32 v37, v46, v47
	global_store_dwordx4 v[44:45], v[34:37], off
	s_nop 1
	v_add_u32_e32 v36, 0x800, v43
	v_add_u32_e32 v43, 0xc00, v43
	ds_read2_b32 v[34:35], v36 offset0:8 offset1:73
	ds_read2_b32 v[36:37], v36 offset0:138 offset1:203
	ds_read2_b32 v[46:47], v43 offset0:12 offset1:77
	ds_read2_b32 v[48:49], v43 offset0:142 offset1:207
	s_waitcnt lgkmcnt(3)
	v_cvt_pk_bf16_f32 v34, v34, v35
	s_waitcnt lgkmcnt(2)
	v_cvt_pk_bf16_f32 v35, v36, v37
	s_waitcnt lgkmcnt(1)
	v_cvt_pk_bf16_f32 v36, v46, v47
	s_waitcnt lgkmcnt(0)
	v_cvt_pk_bf16_f32 v37, v48, v49
	global_store_dwordx4 v[44:45], v[34:37], off offset:16
	s_barrier

.LBB0_514:
	s_andn2_b64 vcc, exec, s[0:1]
	s_cbranch_vccnz .LBB0_516
	s_add_i32 s0, s20, 0xfffffa00
	s_lshr_b32 s88, s0, 6
	v_readlane_b32 s56, v253, 48
	s_lshl_b64 s[0:1], s[88:89], 20
	v_readlane_b32 s64, v253, 56
	v_readlane_b32 s65, v253, 57
	s_add_u32 s27, s64, s0
	v_readlane_b32 s57, v253, 49
	v_readlane_b32 s58, v253, 50
	v_readlane_b32 s59, v253, 51
	v_readlane_b32 s60, v253, 52
	v_readlane_b32 s61, v253, 53
	v_readlane_b32 s62, v253, 54
	v_readlane_b32 s63, v253, 55
	v_readlane_b32 s66, v253, 58
	v_readlane_b32 s67, v253, 59
	v_readlane_b32 s68, v253, 60
	v_readlane_b32 s69, v253, 61
	v_readlane_b32 s70, v253, 62
	v_readlane_b32 s71, v253, 63
	s_addc_u32 s29, s65, s1
	s_lshl_b32 s0, s20, 6
	s_and_b32 s23, s0, 0xc0
	s_lshl_b32 s0, s20, 4
	v_readlane_b32 s56, v253, 0
	s_and_b32 s26, s0, 0x3c0
	s_lshl_b64 s[0:1], s[88:89], 19
	v_readlane_b32 s60, v253, 4
	v_readlane_b32 s61, v253, 5
	s_add_u32 s0, s60, s0
	v_mov_b32_e32 v43, v218
	s_addc_u32 s1, s61, s1
	s_lshl_b32 s28, s26, 2
	v_ashrrev_i32_e32 v36, 4, v43
	s_add_u32 s28, s27, s28
	v_lshlrev_b32_e32 v48, 4, v43
	v_add_u32_e32 v46, s23, v36
	s_addc_u32 s29, s29, 0
	v_and_b32_e32 v184, 0xf0, v48
	v_ashrrev_i32_e32 v47, 31, v46
	v_lshl_add_u64 v[44:45], s[28:29], 0, v[184:185]
	v_lshlrev_b64 v[34:35], 12, v[46:47]
	v_lshl_add_u64 v[34:35], v[44:45], 0, v[34:35]
	v_mul_lo_u32 v36, v36, s34
	v_add3_u32 v47, s2, v36, v184
	global_load_dwordx4 v[60:63], v[34:35], off nt
	s_lshl_b32 s88, s23, 1
	v_readlane_b32 s70, v253, 14
	v_readlane_b32 s71, v253, 15
	s_mov_b32 s71, 0x42ce8ed0
	s_mov_b32 s70, 0xbfb8aa3b
	v_readlane_b32 s57, v253, 1
	v_readlane_b32 s58, v253, 2
	v_readlane_b32 s59, v253, 3
	v_readlane_b32 s62, v253, 6
	v_readlane_b32 s63, v253, 7
	v_readlane_b32 s64, v253, 8
	v_readlane_b32 s65, v253, 9
	v_readlane_b32 s66, v253, 10
	v_readlane_b32 s67, v253, 11
	v_readlane_b32 s68, v253, 12
	v_readlane_b32 s69, v253, 13
	v_add_u32_e32 v34, 16, v46
	v_ashrrev_i32_e32 v35, 31, v34
	v_lshlrev_b64 v[34:35], 12, v[34:35]
	v_lshl_add_u64 v[34:35], v[44:45], 0, v[34:35]
	global_load_dwordx4 v[64:67], v[34:35], off nt
	v_add_u32_e32 v34, 32, v46
	v_ashrrev_i32_e32 v35, 31, v34
	v_lshlrev_b64 v[34:35], 12, v[34:35]
	v_lshl_add_u64 v[34:35], v[44:45], 0, v[34:35]
	global_load_dwordx4 v[68:71], v[34:35], off nt
	v_add_u32_e32 v34, 48, v46
	v_ashrrev_i32_e32 v35, 31, v34
	v_lshlrev_b64 v[34:35], 12, v[34:35]
	v_lshl_add_u64 v[34:35], v[44:45], 0, v[34:35]
	global_load_dwordx4 v[72:75], v[34:35], off nt
	s_waitcnt vmcnt(3)
	ds_write2_b32 v47, v60, v61 offset1:1
	ds_write2_b32 v47, v62, v63 offset0:2 offset1:3
	s_waitcnt vmcnt(2)
	v_add_u32_e32 v58, 0x1040, v47
	ds_write2_b32 v58, v64, v65 offset1:1
	v_add_u32_e32 v58, 0x1048, v47
	ds_write2_b32 v58, v66, v67 offset1:1
	s_waitcnt vmcnt(1)
	v_add_u32_e32 v58, 0x2080, v47
	ds_write2_b32 v58, v68, v69 offset1:1
	v_add_u32_e32 v58, 0x2088, v47
	ds_write2_b32 v58, v70, v71 offset1:1
	s_waitcnt vmcnt(0)
	v_add_u32_e32 v58, 0x30c0, v47
	ds_write2_b32 v58, v72, v73 offset1:1
	v_add_u32_e32 v58, 0x30c8, v47
	ds_write2_b32 v58, v74, v75 offset1:1
	v_ashrrev_i32_e32 v34, 2, v43
	v_and_b32_e32 v36, 48, v48
	v_mul_u32_u24_e32 v35, 0x104, v36
	v_and_b32_e32 v37, -4, v43
	v_add_u32_e32 v34, s26, v34
	v_add3_u32 v43, s2, v35, v37
	v_ashrrev_i32_e32 v35, 31, v34
	v_lshlrev_b64 v[34:35], 9, v[34:35]
	v_lshl_add_u64 v[34:35], s[0:1], 0, v[34:35]
	v_lshl_add_u64 v[34:35], v[34:35], 0, s[88:89]
	v_lshlrev_b32_e32 v184, 1, v36
	s_waitcnt lgkmcnt(0)
	s_barrier
	v_lshl_add_u64 v[44:45], v[34:35], 0, v[184:185]
	ds_read2_b32 v[34:35], v43 offset1:65
	ds_read2_b32 v[36:37], v43 offset0:130 offset1:195
	v_add_u32_e32 v46, 0x400, v43
	s_waitcnt lgkmcnt(1)
	v_cvt_pk_bf16_f32 v34, v34, v35
	s_waitcnt lgkmcnt(0)
	v_cvt_pk_bf16_f32 v35, v36, v37
	ds_read2_b32 v[36:37], v46 offset0:4 offset1:69
	s_waitcnt lgkmcnt(0)
	v_cvt_pk_bf16_f32 v36, v36, v37
	ds_read2_b32 v[46:47], v46 offset0:134 offset1:199
	s_waitcnt lgkmcnt(0)
	v_cvt_pk_bf16_f32 v37, v46, v47
	global_store_dwordx4 v[44:45], v[34:37], off
	s_nop 1
	v_add_u32_e32 v36, 0x800, v43
	v_add_u32_e32 v43, 0xc00, v43
	ds_read2_b32 v[34:35], v36 offset0:8 offset1:73
	ds_read2_b32 v[36:37], v36 offset0:138 offset1:203
	ds_read2_b32 v[46:47], v43 offset0:12 offset1:77
	ds_read2_b32 v[48:49], v43 offset0:142 offset1:207
	s_waitcnt lgkmcnt(3)
	v_cvt_pk_bf16_f32 v34, v34, v35
	s_waitcnt lgkmcnt(2)
	v_cvt_pk_bf16_f32 v35, v36, v37
	s_waitcnt lgkmcnt(1)
	v_cvt_pk_bf16_f32 v36, v46, v47
	s_waitcnt lgkmcnt(0)
	v_cvt_pk_bf16_f32 v37, v48, v49
	global_store_dwordx4 v[44:45], v[34:37], off offset:16
	s_barrier

.LBB0_517:
	s_lshl_b32 s0, s20, 2
	s_and_b32 s23, s0, 0xffffffc0
	s_add_i32 s0, s23, 0x100
	s_cmpk_lt_i32 s23, 0x700
	s_cselect_b32 s0, s23, s0
	s_lshl_b32 s1, s20, 6
	s_and_b32 s26, s1, 0x3c0
	s_ashr_i32 s1, s0, 31
	v_readlane_b32 s4, v253, 32
	v_mov_b32_e32 v43, v218
	s_lshl_b64 s[0:1], s[0:1], 2
	v_readlane_b32 s18, v253, 46
	v_readlane_b32 s19, v253, 47
	s_add_u32 s0, s18, s0
	v_lshlrev_b32_e32 v46, 4, v43
	v_ashrrev_i32_e32 v36, 4, v43
	s_addc_u32 s1, s19, s1
	v_and_b32_e32 v184, 0xf0, v46
	v_lshl_add_u64 v[44:45], s[0:1], 0, v[184:185]
	v_add_u32_e32 v47, s26, v36
	v_mad_i64_i32 v[34:35], s[0:1], v47, s35, v[44:45]
	v_mul_lo_u32 v36, v36, s34
	v_add3_u32 v48, s2, v36, v184
	global_load_dwordx4 v[60:63], v[34:35], off nt
	v_readlane_b32 s5, v253, 33
	v_readlane_b32 s6, v253, 34
	v_readlane_b32 s7, v253, 35
	v_readlane_b32 s8, v253, 36
	v_readlane_b32 s9, v253, 37
	v_readlane_b32 s10, v253, 38
	v_readlane_b32 s11, v253, 39
	v_readlane_b32 s12, v253, 40
	v_readlane_b32 s13, v253, 41
	v_readlane_b32 s14, v253, 42
	v_readlane_b32 s15, v253, 43
	v_readlane_b32 s16, v253, 44
	v_readlane_b32 s17, v253, 45
	v_readlane_b32 s4, v253, 0
	v_readlane_b32 s6, v253, 2
	v_readlane_b32 s7, v253, 3
	s_lshl_b32 s88, s26, 1
	v_readlane_b32 s5, v253, 1
	v_readlane_b32 s8, v253, 4
	v_readlane_b32 s9, v253, 5
	v_readlane_b32 s10, v253, 6
	v_readlane_b32 s11, v253, 7
	v_readlane_b32 s12, v253, 8
	v_readlane_b32 s13, v253, 9
	v_readlane_b32 s14, v253, 10
	v_readlane_b32 s15, v253, 11
	v_readlane_b32 s16, v253, 12
	v_readlane_b32 s17, v253, 13
	v_readlane_b32 s18, v253, 14
	v_readlane_b32 s19, v253, 15
	v_add_u32_e32 v34, 16, v47
	v_mad_i64_i32 v[34:35], s[0:1], v34, s35, v[44:45]
	global_load_dwordx4 v[64:67], v[34:35], off nt
	v_add_u32_e32 v34, 32, v47
	v_mad_i64_i32 v[34:35], s[0:1], v34, s35, v[44:45]
	global_load_dwordx4 v[68:71], v[34:35], off nt
	v_add_u32_e32 v34, 48, v47
	v_mad_i64_i32 v[34:35], s[0:1], v34, s35, v[44:45]
	global_load_dwordx4 v[72:75], v[34:35], off nt
	s_waitcnt vmcnt(3)
	ds_write2_b32 v48, v60, v61 offset1:1
	ds_write2_b32 v48, v62, v63 offset0:2 offset1:3
	s_waitcnt vmcnt(2)
	v_add_u32_e32 v58, 0x1040, v48
	ds_write2_b32 v58, v64, v65 offset1:1
	v_add_u32_e32 v58, 0x1048, v48
	ds_write2_b32 v58, v66, v67 offset1:1
	s_waitcnt vmcnt(1)
	v_add_u32_e32 v58, 0x2080, v48
	ds_write2_b32 v58, v68, v69 offset1:1
	v_add_u32_e32 v58, 0x2088, v48
	ds_write2_b32 v58, v70, v71 offset1:1
	s_waitcnt vmcnt(0)
	v_add_u32_e32 v58, 0x30c0, v48
	ds_write2_b32 v58, v72, v73 offset1:1
	v_add_u32_e32 v58, 0x30c8, v48
	ds_write2_b32 v58, v74, v75 offset1:1
	v_ashrrev_i32_e32 v34, 2, v43
	v_and_b32_e32 v36, 48, v46
	v_mul_u32_u24_e32 v35, 0x104, v36
	v_and_b32_e32 v37, -4, v43
	v_add_u32_e32 v34, s23, v34
	v_add3_u32 v43, s2, v35, v37
	v_ashrrev_i32_e32 v35, 31, v34
	v_lshlrev_b64 v[34:35], 11, v[34:35]
	v_lshl_add_u64 v[34:35], s[6:7], 0, v[34:35]
	v_lshl_add_u64 v[34:35], v[34:35], 0, s[88:89]
	v_lshlrev_b32_e32 v184, 1, v36
	s_waitcnt lgkmcnt(0)
	s_barrier
	v_lshl_add_u64 v[44:45], v[34:35], 0, v[184:185]
	ds_read2_b32 v[34:35], v43 offset1:65
	ds_read2_b32 v[36:37], v43 offset0:130 offset1:195
	v_add_u32_e32 v46, 0x400, v43
	s_waitcnt lgkmcnt(1)
	v_cvt_pk_bf16_f32 v34, v34, v35
	s_waitcnt lgkmcnt(0)
	v_cvt_pk_bf16_f32 v35, v36, v37
	ds_read2_b32 v[36:37], v46 offset0:4 offset1:69
	s_waitcnt lgkmcnt(0)
	v_cvt_pk_bf16_f32 v36, v36, v37
	ds_read2_b32 v[46:47], v46 offset0:134 offset1:199
	s_waitcnt lgkmcnt(0)
	v_cvt_pk_bf16_f32 v37, v46, v47
	global_store_dwordx4 v[44:45], v[34:37], off
	s_nop 1
	v_add_u32_e32 v36, 0x800, v43
	v_add_u32_e32 v43, 0xc00, v43
	ds_read2_b32 v[34:35], v36 offset0:8 offset1:73
	ds_read2_b32 v[36:37], v36 offset0:138 offset1:203
	ds_read2_b32 v[46:47], v43 offset0:12 offset1:77
	ds_read2_b32 v[48:49], v43 offset0:142 offset1:207
	s_waitcnt lgkmcnt(3)
	v_cvt_pk_bf16_f32 v34, v34, v35
	s_waitcnt lgkmcnt(2)
	v_cvt_pk_bf16_f32 v35, v36, v37
	s_waitcnt lgkmcnt(1)
	v_cvt_pk_bf16_f32 v36, v46, v47
	s_waitcnt lgkmcnt(0)
	v_cvt_pk_bf16_f32 v37, v48, v49
	global_store_dwordx4 v[44:45], v[34:37], off offset:16
	s_barrier
	s_branch .LBB0_484
